# U sweep reduction: diagonal extraction + 4x4 quad transpose-sum (21 VALU per batch) replaced by 12 quad-broadcast DPP adds + 3 selects (15 VALU), same summation order; on top of v058
# speedup vs baseline: 1.0116x; 1.0116x over previous
.Lus_loop:
	s_barrier
	s_waitcnt vmcnt(12) lgkmcnt(10)
	v_mul_f32_e32 v1, v140, v83
	v_add_f32_dpp v184, v185, v184 quad_perm:[1,1,1,1] row_mask:0xf bank_mask:0xf bound_ctrl:1
	v_add_f32_dpp v186, v187, v186 quad_perm:[3,3,3,3] row_mask:0xf bank_mask:0xf bound_ctrl:1
	v_mfma_f32_16x16x32_fp8_fp8 v[200:203], v[18:19], v[118:119], 0
	v_add_f32_dpp v189, v188, v189 quad_perm:[0,0,0,0] row_mask:0xf bank_mask:0xf bound_ctrl:1
	v_add_f32_dpp v190, v191, v190 quad_perm:[3,3,3,3] row_mask:0xf bank_mask:0xf bound_ctrl:1
	v_mfma_f32_16x16x32_fp8_fp8 v[204:207], v[22:23], v[118:119], 0
	v_add_f32_dpp v194, v195, v194 quad_perm:[3,3,3,3] row_mask:0xf bank_mask:0xf bound_ctrl:1
	v_add_f32_dpp v192, v193, v192 quad_perm:[1,1,1,1] row_mask:0xf bank_mask:0xf bound_ctrl:1
	v_mfma_f32_16x16x32_fp8_fp8 v[228:231], v[26:27], v[118:119], 0
	v_add_f32_dpp v199, v198, v199 quad_perm:[2,2,2,2] row_mask:0xf bank_mask:0xf bound_ctrl:1
	v_add_f32_dpp v196, v197, v196 quad_perm:[1,1,1,1] row_mask:0xf bank_mask:0xf bound_ctrl:1
	v_mfma_f32_16x16x32_fp8_fp8 v[232:235], v[30:31], v[118:119], 0
	v_add_f32_dpp v184, v186, v184 quad_perm:[2,2,2,2] row_mask:0xf bank_mask:0xf bound_ctrl:1
	v_add_f32_dpp v189, v190, v189 quad_perm:[2,2,2,2] row_mask:0xf bank_mask:0xf bound_ctrl:1
	v_mfma_f32_16x16x32_fp8_fp8 v[200:203], v[20:21], v[120:121], v[200:203]
	v_add_f32_dpp v194, v192, v194 quad_perm:[0,0,0,0] row_mask:0xf bank_mask:0xf bound_ctrl:1
	v_add_f32_dpp v199, v196, v199 quad_perm:[0,0,0,0] row_mask:0xf bank_mask:0xf bound_ctrl:1
	v_mfma_f32_16x16x32_fp8_fp8 v[204:207], v[24:25], v[120:121], v[204:207]
	v_cndmask_b32_e64 v146, v189, v184, s[2:3]
	v_cndmask_b32_e64 v142, v199, v194, s[2:3]
	v_mfma_f32_16x16x32_fp8_fp8 v[228:231], v[28:29], v[120:121], v[228:231]
	v_cndmask_b32_e64 v86, v142, v146, s[4:5]
	v_mfma_f32_16x16x32_fp8_fp8 v[232:235], v[32:33], v[120:121], v[232:235]
	v_lshl_add_u32 v145, v70, 10, v92
	global_load_dwordx4 v[18:21], v145, s[98:99]
	v_cndmask_b32_e64 v86, 0, v86, s[6:7]
	v_lshl_add_u32 v147, v71, 10, v92
	global_load_dwordx4 v[22:25], v147, s[98:99]
	v_add_f32_dpp v86, v86, v86 row_ror:4 row_mask:0xf bank_mask:0xf bound_ctrl:1
	v_lshl_add_u32 v145, v72, 10, v92
	global_load_dwordx4 v[26:29], v145, s[98:99]
	v_add_f32_dpp v86, v86, v86 row_ror:8 row_mask:0xf bank_mask:0xf bound_ctrl:1
	v_mov_b32_e32 v87, v86
	v_lshl_add_u32 v147, v73, 10, v92
	global_load_dwordx4 v[30:33], v147, s[98:99]
	v_permlane16_swap_b32_e32 v86, v87
	v_add_f32_e32 v86, v86, v87
	v_mov_b32_e32 v87, v86
	ds_read_b32 v83, v89 offset:8704
	ds_read_b128 v[70:73], v91 offset:1536
	v_permlane32_swap_b32 v86, v87
	v_add_f32_e32 v86, v86, v87
	v_mul_f32_e32 v93, v88, v86
	s_mov_b64 exec, s[8:9]
	ds_write_b32 v89, v93 offset:1024
	s_mov_b64 exec, -1
	s_waitcnt vmcnt(12) lgkmcnt(10)
	v_mul_f32_e32 v88, v139, v84
	v_add_f32_dpp v200, v201, v200 quad_perm:[1,1,1,1] row_mask:0xf bank_mask:0xf bound_ctrl:1
	v_add_f32_dpp v202, v203, v202 quad_perm:[3,3,3,3] row_mask:0xf bank_mask:0xf bound_ctrl:1
	v_mfma_f32_16x16x32_fp8_fp8 v[184:187], v[34:35], v[114:115], 0
	v_add_f32_dpp v205, v204, v205 quad_perm:[0,0,0,0] row_mask:0xf bank_mask:0xf bound_ctrl:1
	v_add_f32_dpp v206, v207, v206 quad_perm:[3,3,3,3] row_mask:0xf bank_mask:0xf bound_ctrl:1
	v_mfma_f32_16x16x32_fp8_fp8 v[188:191], v[38:39], v[114:115], 0
	v_add_f32_dpp v230, v231, v230 quad_perm:[3,3,3,3] row_mask:0xf bank_mask:0xf bound_ctrl:1
	v_add_f32_dpp v228, v229, v228 quad_perm:[1,1,1,1] row_mask:0xf bank_mask:0xf bound_ctrl:1
	v_mfma_f32_16x16x32_fp8_fp8 v[192:195], v[42:43], v[114:115], 0
	v_add_f32_dpp v235, v234, v235 quad_perm:[2,2,2,2] row_mask:0xf bank_mask:0xf bound_ctrl:1
	v_add_f32_dpp v232, v233, v232 quad_perm:[1,1,1,1] row_mask:0xf bank_mask:0xf bound_ctrl:1
	v_mfma_f32_16x16x32_fp8_fp8 v[196:199], v[46:47], v[114:115], 0
	v_add_f32_dpp v200, v202, v200 quad_perm:[2,2,2,2] row_mask:0xf bank_mask:0xf bound_ctrl:1
	v_add_f32_dpp v205, v206, v205 quad_perm:[2,2,2,2] row_mask:0xf bank_mask:0xf bound_ctrl:1
	v_mfma_f32_16x16x32_fp8_fp8 v[184:187], v[36:37], v[116:117], v[184:187]
	v_add_f32_dpp v230, v228, v230 quad_perm:[0,0,0,0] row_mask:0xf bank_mask:0xf bound_ctrl:1
	v_add_f32_dpp v235, v232, v235 quad_perm:[0,0,0,0] row_mask:0xf bank_mask:0xf bound_ctrl:1
	v_mfma_f32_16x16x32_fp8_fp8 v[188:191], v[40:41], v[116:117], v[188:191]
	v_cndmask_b32_e64 v146, v205, v200, s[2:3]
	v_cndmask_b32_e64 v142, v235, v230, s[2:3]
	v_mfma_f32_16x16x32_fp8_fp8 v[192:195], v[44:45], v[116:117], v[192:195]
	v_cndmask_b32_e64 v86, v142, v146, s[4:5]
	v_mfma_f32_16x16x32_fp8_fp8 v[196:199], v[48:49], v[116:117], v[196:199]
	v_lshl_add_u32 v145, v74, 10, v92
	global_load_dwordx4 v[34:37], v145, s[98:99]
	v_cndmask_b32_e64 v86, 0, v86, s[6:7]
	v_lshl_add_u32 v147, v75, 10, v92
	global_load_dwordx4 v[38:41], v147, s[98:99]
	v_add_f32_dpp v86, v86, v86 row_ror:4 row_mask:0xf bank_mask:0xf bound_ctrl:1
	v_lshl_add_u32 v145, v76, 10, v92
	global_load_dwordx4 v[42:45], v145, s[98:99]
	v_add_f32_dpp v86, v86, v86 row_ror:8 row_mask:0xf bank_mask:0xf bound_ctrl:1
	v_mov_b32_e32 v87, v86
	v_lshl_add_u32 v147, v77, 10, v92
	global_load_dwordx4 v[46:49], v147, s[98:99]
	v_permlane16_swap_b32_e32 v86, v87
	v_add_f32_e32 v86, v86, v87
	v_mov_b32_e32 v87, v86
	ds_read_b32 v84, v89 offset:10240
	ds_read_b128 v[74:77], v91 offset:3072
	v_permlane32_swap_b32 v86, v87
	v_add_f32_e32 v86, v86, v87
	v_mul_f32_e32 v93, v1, v86
	s_mov_b64 exec, s[8:9]
	ds_write_b32 v89, v93 offset:2560
	s_mov_b64 exec, -1
	s_waitcnt vmcnt(12) lgkmcnt(10)
	v_mul_f32_e32 v1, v138, v85
	v_add_f32_dpp v184, v185, v184 quad_perm:[1,1,1,1] row_mask:0xf bank_mask:0xf bound_ctrl:1
	v_add_f32_dpp v186, v187, v186 quad_perm:[3,3,3,3] row_mask:0xf bank_mask:0xf bound_ctrl:1
	v_mfma_f32_16x16x32_fp8_fp8 v[200:203], v[50:51], v[110:111], 0
	v_add_f32_dpp v189, v188, v189 quad_perm:[0,0,0,0] row_mask:0xf bank_mask:0xf bound_ctrl:1
	v_add_f32_dpp v190, v191, v190 quad_perm:[3,3,3,3] row_mask:0xf bank_mask:0xf bound_ctrl:1
	v_mfma_f32_16x16x32_fp8_fp8 v[204:207], v[54:55], v[110:111], 0
	v_add_f32_dpp v194, v195, v194 quad_perm:[3,3,3,3] row_mask:0xf bank_mask:0xf bound_ctrl:1
	v_add_f32_dpp v192, v193, v192 quad_perm:[1,1,1,1] row_mask:0xf bank_mask:0xf bound_ctrl:1
	v_mfma_f32_16x16x32_fp8_fp8 v[228:231], v[58:59], v[110:111], 0
	v_add_f32_dpp v199, v198, v199 quad_perm:[2,2,2,2] row_mask:0xf bank_mask:0xf bound_ctrl:1
	v_add_f32_dpp v196, v197, v196 quad_perm:[1,1,1,1] row_mask:0xf bank_mask:0xf bound_ctrl:1
	v_mfma_f32_16x16x32_fp8_fp8 v[232:235], v[62:63], v[110:111], 0
	v_add_f32_dpp v184, v186, v184 quad_perm:[2,2,2,2] row_mask:0xf bank_mask:0xf bound_ctrl:1
	v_add_f32_dpp v189, v190, v189 quad_perm:[2,2,2,2] row_mask:0xf bank_mask:0xf bound_ctrl:1
	v_mfma_f32_16x16x32_fp8_fp8 v[200:203], v[52:53], v[112:113], v[200:203]
	v_add_f32_dpp v194, v192, v194 quad_perm:[0,0,0,0] row_mask:0xf bank_mask:0xf bound_ctrl:1
	v_add_f32_dpp v199, v196, v199 quad_perm:[0,0,0,0] row_mask:0xf bank_mask:0xf bound_ctrl:1
	v_mfma_f32_16x16x32_fp8_fp8 v[204:207], v[56:57], v[112:113], v[204:207]
	v_cndmask_b32_e64 v146, v189, v184, s[2:3]
	v_cndmask_b32_e64 v142, v199, v194, s[2:3]
	v_mfma_f32_16x16x32_fp8_fp8 v[228:231], v[60:61], v[112:113], v[228:231]
	v_cndmask_b32_e64 v86, v142, v146, s[4:5]
	v_mfma_f32_16x16x32_fp8_fp8 v[232:235], v[64:65], v[112:113], v[232:235]
	v_lshl_add_u32 v145, v78, 10, v92
	global_load_dwordx4 v[50:53], v145, s[98:99]
	v_cndmask_b32_e64 v86, 0, v86, s[6:7]
	v_lshl_add_u32 v147, v79, 10, v92
	global_load_dwordx4 v[54:57], v147, s[98:99]
	v_add_f32_dpp v86, v86, v86 row_ror:4 row_mask:0xf bank_mask:0xf bound_ctrl:1
	v_lshl_add_u32 v145, v80, 10, v92
	global_load_dwordx4 v[58:61], v145, s[98:99]
	v_add_f32_dpp v86, v86, v86 row_ror:8 row_mask:0xf bank_mask:0xf bound_ctrl:1
	v_mov_b32_e32 v87, v86
	v_lshl_add_u32 v147, v81, 10, v92
	global_load_dwordx4 v[62:65], v147, s[98:99]
	v_permlane16_swap_b32_e32 v86, v87
	v_add_f32_e32 v86, v86, v87
	v_mov_b32_e32 v87, v86
	ds_read_b32 v85, v89 offset:11776
	ds_read_b128 v[78:81], v91 offset:4608
	v_permlane32_swap_b32 v86, v87
	v_add_f32_e32 v86, v86, v87
	v_mul_f32_e32 v93, v88, v86
	s_mov_b64 exec, s[8:9]
	ds_write_b32 v89, v93 offset:4096
	s_mov_b64 exec, -1
	s_waitcnt vmcnt(12) lgkmcnt(10)
	v_mul_f32_e32 v88, v137, v82
	v_add_f32_dpp v200, v201, v200 quad_perm:[1,1,1,1] row_mask:0xf bank_mask:0xf bound_ctrl:1
	v_add_f32_dpp v202, v203, v202 quad_perm:[3,3,3,3] row_mask:0xf bank_mask:0xf bound_ctrl:1
	v_mfma_f32_16x16x32_fp8_fp8 v[184:187], v[2:3], v[106:107], 0
	v_add_f32_dpp v205, v204, v205 quad_perm:[0,0,0,0] row_mask:0xf bank_mask:0xf bound_ctrl:1
	v_add_f32_dpp v206, v207, v206 quad_perm:[3,3,3,3] row_mask:0xf bank_mask:0xf bound_ctrl:1
	v_mfma_f32_16x16x32_fp8_fp8 v[188:191], v[6:7], v[106:107], 0
	v_add_f32_dpp v230, v231, v230 quad_perm:[3,3,3,3] row_mask:0xf bank_mask:0xf bound_ctrl:1
	v_add_f32_dpp v228, v229, v228 quad_perm:[1,1,1,1] row_mask:0xf bank_mask:0xf bound_ctrl:1
	v_mfma_f32_16x16x32_fp8_fp8 v[192:195], v[10:11], v[106:107], 0
	v_add_f32_dpp v235, v234, v235 quad_perm:[2,2,2,2] row_mask:0xf bank_mask:0xf bound_ctrl:1
	v_add_f32_dpp v232, v233, v232 quad_perm:[1,1,1,1] row_mask:0xf bank_mask:0xf bound_ctrl:1
	v_mfma_f32_16x16x32_fp8_fp8 v[196:199], v[14:15], v[106:107], 0
	v_add_f32_dpp v200, v202, v200 quad_perm:[2,2,2,2] row_mask:0xf bank_mask:0xf bound_ctrl:1
	v_add_f32_dpp v205, v206, v205 quad_perm:[2,2,2,2] row_mask:0xf bank_mask:0xf bound_ctrl:1
	v_mfma_f32_16x16x32_fp8_fp8 v[184:187], v[4:5], v[108:109], v[184:187]
	v_add_f32_dpp v230, v228, v230 quad_perm:[0,0,0,0] row_mask:0xf bank_mask:0xf bound_ctrl:1
	v_add_f32_dpp v235, v232, v235 quad_perm:[0,0,0,0] row_mask:0xf bank_mask:0xf bound_ctrl:1
	v_mfma_f32_16x16x32_fp8_fp8 v[188:191], v[8:9], v[108:109], v[188:191]
	v_cndmask_b32_e64 v146, v205, v200, s[2:3]
	v_cndmask_b32_e64 v142, v235, v230, s[2:3]
	v_mfma_f32_16x16x32_fp8_fp8 v[192:195], v[12:13], v[108:109], v[192:195]
	v_cndmask_b32_e64 v86, v142, v146, s[4:5]
	v_mfma_f32_16x16x32_fp8_fp8 v[196:199], v[16:17], v[108:109], v[196:199]
	v_lshl_add_u32 v145, v66, 10, v92
	global_load_dwordx4 v[2:5], v145, s[98:99]
	v_cndmask_b32_e64 v86, 0, v86, s[6:7]
	v_lshl_add_u32 v147, v67, 10, v92
	global_load_dwordx4 v[6:9], v147, s[98:99]
	v_add_f32_dpp v86, v86, v86 row_ror:4 row_mask:0xf bank_mask:0xf bound_ctrl:1
	v_lshl_add_u32 v145, v68, 10, v92
	global_load_dwordx4 v[10:13], v145, s[98:99]
	v_add_f32_dpp v86, v86, v86 row_ror:8 row_mask:0xf bank_mask:0xf bound_ctrl:1
	v_mov_b32_e32 v87, v86
	v_lshl_add_u32 v147, v69, 10, v92
	global_load_dwordx4 v[14:17], v147, s[98:99]
	v_permlane16_swap_b32_e32 v86, v87
	v_add_f32_e32 v86, v86, v87
	v_mov_b32_e32 v87, v86
	ds_read_b32 v82, v90 offset:1024
	ds_read_b128 v[66:69], v91 offset:6144
	v_permlane32_swap_b32 v86, v87
	v_add_f32_e32 v86, v86, v87
	v_mul_f32_e32 v93, v1, v86
	s_mov_b64 exec, s[8:9]
	ds_write_b32 v89, v93 offset:5632
	s_mov_b64 exec, -1
	s_waitcnt vmcnt(12) lgkmcnt(10)
	v_mul_f32_e32 v1, v136, v83
	v_add_f32_dpp v184, v185, v184 quad_perm:[1,1,1,1] row_mask:0xf bank_mask:0xf bound_ctrl:1
	v_add_f32_dpp v186, v187, v186 quad_perm:[3,3,3,3] row_mask:0xf bank_mask:0xf bound_ctrl:1
	v_mfma_f32_16x16x32_fp8_fp8 v[200:203], v[18:19], v[102:103], 0
	v_add_f32_dpp v189, v188, v189 quad_perm:[0,0,0,0] row_mask:0xf bank_mask:0xf bound_ctrl:1
	v_add_f32_dpp v190, v191, v190 quad_perm:[3,3,3,3] row_mask:0xf bank_mask:0xf bound_ctrl:1
	v_mfma_f32_16x16x32_fp8_fp8 v[204:207], v[22:23], v[102:103], 0
	v_add_f32_dpp v194, v195, v194 quad_perm:[3,3,3,3] row_mask:0xf bank_mask:0xf bound_ctrl:1
	v_add_f32_dpp v192, v193, v192 quad_perm:[1,1,1,1] row_mask:0xf bank_mask:0xf bound_ctrl:1
	v_mfma_f32_16x16x32_fp8_fp8 v[228:231], v[26:27], v[102:103], 0
	v_add_f32_dpp v199, v198, v199 quad_perm:[2,2,2,2] row_mask:0xf bank_mask:0xf bound_ctrl:1
	v_add_f32_dpp v196, v197, v196 quad_perm:[1,1,1,1] row_mask:0xf bank_mask:0xf bound_ctrl:1
	v_mfma_f32_16x16x32_fp8_fp8 v[232:235], v[30:31], v[102:103], 0
	v_add_f32_dpp v184, v186, v184 quad_perm:[2,2,2,2] row_mask:0xf bank_mask:0xf bound_ctrl:1
	v_add_f32_dpp v189, v190, v189 quad_perm:[2,2,2,2] row_mask:0xf bank_mask:0xf bound_ctrl:1
	v_mfma_f32_16x16x32_fp8_fp8 v[200:203], v[20:21], v[104:105], v[200:203]
	v_add_f32_dpp v194, v192, v194 quad_perm:[0,0,0,0] row_mask:0xf bank_mask:0xf bound_ctrl:1
	v_add_f32_dpp v199, v196, v199 quad_perm:[0,0,0,0] row_mask:0xf bank_mask:0xf bound_ctrl:1
	v_mfma_f32_16x16x32_fp8_fp8 v[204:207], v[24:25], v[104:105], v[204:207]
	v_cndmask_b32_e64 v146, v189, v184, s[2:3]
	v_cndmask_b32_e64 v142, v199, v194, s[2:3]
	v_mfma_f32_16x16x32_fp8_fp8 v[228:231], v[28:29], v[104:105], v[228:231]
	v_cndmask_b32_e64 v86, v142, v146, s[4:5]
	v_mfma_f32_16x16x32_fp8_fp8 v[232:235], v[32:33], v[104:105], v[232:235]
	v_lshl_add_u32 v145, v70, 10, v92
	global_load_dwordx4 v[18:21], v145, s[98:99]
	v_cndmask_b32_e64 v86, 0, v86, s[6:7]
	v_lshl_add_u32 v147, v71, 10, v92
	global_load_dwordx4 v[22:25], v147, s[98:99]
	v_add_f32_dpp v86, v86, v86 row_ror:4 row_mask:0xf bank_mask:0xf bound_ctrl:1
	v_lshl_add_u32 v145, v72, 10, v92
	global_load_dwordx4 v[26:29], v145, s[98:99]
	v_add_f32_dpp v86, v86, v86 row_ror:8 row_mask:0xf bank_mask:0xf bound_ctrl:1
	v_mov_b32_e32 v87, v86
	v_lshl_add_u32 v147, v73, 10, v92
	global_load_dwordx4 v[30:33], v147, s[98:99]
	v_permlane16_swap_b32_e32 v86, v87
	v_add_f32_e32 v86, v86, v87
	v_mov_b32_e32 v87, v86
	ds_read_b32 v83, v90 offset:2560
	ds_read_b128 v[70:73], v91 offset:7680
	v_permlane32_swap_b32 v86, v87
	v_add_f32_e32 v86, v86, v87
	v_mul_f32_e32 v93, v88, v86
	s_mov_b64 exec, s[8:9]
	ds_write_b32 v89, v93 offset:7168
	s_mov_b64 exec, -1
	s_waitcnt vmcnt(12) lgkmcnt(10)
	v_mul_f32_e32 v88, v129, v84
	v_add_f32_dpp v200, v201, v200 quad_perm:[1,1,1,1] row_mask:0xf bank_mask:0xf bound_ctrl:1
	v_add_f32_dpp v202, v203, v202 quad_perm:[3,3,3,3] row_mask:0xf bank_mask:0xf bound_ctrl:1
	v_mfma_f32_16x16x32_fp8_fp8 v[184:187], v[34:35], v[98:99], 0
	v_add_f32_dpp v205, v204, v205 quad_perm:[0,0,0,0] row_mask:0xf bank_mask:0xf bound_ctrl:1
	v_add_f32_dpp v206, v207, v206 quad_perm:[3,3,3,3] row_mask:0xf bank_mask:0xf bound_ctrl:1
	v_mfma_f32_16x16x32_fp8_fp8 v[188:191], v[38:39], v[98:99], 0
	v_add_f32_dpp v230, v231, v230 quad_perm:[3,3,3,3] row_mask:0xf bank_mask:0xf bound_ctrl:1
	v_add_f32_dpp v228, v229, v228 quad_perm:[1,1,1,1] row_mask:0xf bank_mask:0xf bound_ctrl:1
	v_mfma_f32_16x16x32_fp8_fp8 v[192:195], v[42:43], v[98:99], 0
	v_add_f32_dpp v235, v234, v235 quad_perm:[2,2,2,2] row_mask:0xf bank_mask:0xf bound_ctrl:1
	v_add_f32_dpp v232, v233, v232 quad_perm:[1,1,1,1] row_mask:0xf bank_mask:0xf bound_ctrl:1
	v_mfma_f32_16x16x32_fp8_fp8 v[196:199], v[46:47], v[98:99], 0
	v_add_f32_dpp v200, v202, v200 quad_perm:[2,2,2,2] row_mask:0xf bank_mask:0xf bound_ctrl:1
	v_add_f32_dpp v205, v206, v205 quad_perm:[2,2,2,2] row_mask:0xf bank_mask:0xf bound_ctrl:1
	v_mfma_f32_16x16x32_fp8_fp8 v[184:187], v[36:37], v[100:101], v[184:187]
	v_add_f32_dpp v230, v228, v230 quad_perm:[0,0,0,0] row_mask:0xf bank_mask:0xf bound_ctrl:1
	v_add_f32_dpp v235, v232, v235 quad_perm:[0,0,0,0] row_mask:0xf bank_mask:0xf bound_ctrl:1
	v_mfma_f32_16x16x32_fp8_fp8 v[188:191], v[40:41], v[100:101], v[188:191]
	v_cndmask_b32_e64 v146, v205, v200, s[2:3]
	v_cndmask_b32_e64 v142, v235, v230, s[2:3]
	v_mfma_f32_16x16x32_fp8_fp8 v[192:195], v[44:45], v[100:101], v[192:195]
	v_cndmask_b32_e64 v86, v142, v146, s[4:5]
	v_mfma_f32_16x16x32_fp8_fp8 v[196:199], v[48:49], v[100:101], v[196:199]
	v_lshl_add_u32 v145, v74, 10, v92
	global_load_dwordx4 v[34:37], v145, s[98:99]
	v_cndmask_b32_e64 v86, 0, v86, s[6:7]
	v_lshl_add_u32 v147, v75, 10, v92
	global_load_dwordx4 v[38:41], v147, s[98:99]
	v_add_f32_dpp v86, v86, v86 row_ror:4 row_mask:0xf bank_mask:0xf bound_ctrl:1
	v_lshl_add_u32 v145, v76, 10, v92
	global_load_dwordx4 v[42:45], v145, s[98:99]
	v_add_f32_dpp v86, v86, v86 row_ror:8 row_mask:0xf bank_mask:0xf bound_ctrl:1
	v_mov_b32_e32 v87, v86
	v_lshl_add_u32 v147, v77, 10, v92
	global_load_dwordx4 v[46:49], v147, s[98:99]
	v_permlane16_swap_b32_e32 v86, v87
	v_add_f32_e32 v86, v86, v87
	v_mov_b32_e32 v87, v86
	ds_read_b32 v84, v90 offset:4096
	ds_read_b128 v[74:77], v91 offset:9216
	v_permlane32_swap_b32 v86, v87
	v_add_f32_e32 v86, v86, v87
	v_mul_f32_e32 v93, v1, v86
	s_mov_b64 exec, s[8:9]
	ds_write_b32 v89, v93 offset:8704
	s_mov_b64 exec, -1
	s_waitcnt vmcnt(12) lgkmcnt(10)
	v_mul_f32_e32 v1, v128, v85
	v_add_f32_dpp v184, v185, v184 quad_perm:[1,1,1,1] row_mask:0xf bank_mask:0xf bound_ctrl:1
	v_add_f32_dpp v186, v187, v186 quad_perm:[3,3,3,3] row_mask:0xf bank_mask:0xf bound_ctrl:1
	v_mfma_f32_16x16x32_fp8_fp8 v[200:203], v[50:51], v[94:95], 0
	v_add_f32_dpp v189, v188, v189 quad_perm:[0,0,0,0] row_mask:0xf bank_mask:0xf bound_ctrl:1
	v_add_f32_dpp v190, v191, v190 quad_perm:[3,3,3,3] row_mask:0xf bank_mask:0xf bound_ctrl:1
	v_mfma_f32_16x16x32_fp8_fp8 v[204:207], v[54:55], v[94:95], 0
	v_add_f32_dpp v194, v195, v194 quad_perm:[3,3,3,3] row_mask:0xf bank_mask:0xf bound_ctrl:1
	v_add_f32_dpp v192, v193, v192 quad_perm:[1,1,1,1] row_mask:0xf bank_mask:0xf bound_ctrl:1
	v_mfma_f32_16x16x32_fp8_fp8 v[228:231], v[58:59], v[94:95], 0
	v_add_f32_dpp v199, v198, v199 quad_perm:[2,2,2,2] row_mask:0xf bank_mask:0xf bound_ctrl:1
	v_add_f32_dpp v196, v197, v196 quad_perm:[1,1,1,1] row_mask:0xf bank_mask:0xf bound_ctrl:1
	v_mfma_f32_16x16x32_fp8_fp8 v[232:235], v[62:63], v[94:95], 0
	v_add_f32_dpp v184, v186, v184 quad_perm:[2,2,2,2] row_mask:0xf bank_mask:0xf bound_ctrl:1
	v_add_f32_dpp v189, v190, v189 quad_perm:[2,2,2,2] row_mask:0xf bank_mask:0xf bound_ctrl:1
	v_mfma_f32_16x16x32_fp8_fp8 v[200:203], v[52:53], v[96:97], v[200:203]
	v_add_f32_dpp v194, v192, v194 quad_perm:[0,0,0,0] row_mask:0xf bank_mask:0xf bound_ctrl:1
	v_add_f32_dpp v199, v196, v199 quad_perm:[0,0,0,0] row_mask:0xf bank_mask:0xf bound_ctrl:1
	v_mfma_f32_16x16x32_fp8_fp8 v[204:207], v[56:57], v[96:97], v[204:207]
	v_cndmask_b32_e64 v146, v189, v184, s[2:3]
	v_cndmask_b32_e64 v142, v199, v194, s[2:3]
	v_mfma_f32_16x16x32_fp8_fp8 v[228:231], v[60:61], v[96:97], v[228:231]
	v_cndmask_b32_e64 v86, v142, v146, s[4:5]
	v_mfma_f32_16x16x32_fp8_fp8 v[232:235], v[64:65], v[96:97], v[232:235]
	v_lshl_add_u32 v145, v78, 10, v92
	global_load_dwordx4 v[50:53], v145, s[98:99]
	v_cndmask_b32_e64 v86, 0, v86, s[6:7]
	v_lshl_add_u32 v147, v79, 10, v92
	global_load_dwordx4 v[54:57], v147, s[98:99]
	v_add_f32_dpp v86, v86, v86 row_ror:4 row_mask:0xf bank_mask:0xf bound_ctrl:1
	v_lshl_add_u32 v145, v80, 10, v92
	global_load_dwordx4 v[58:61], v145, s[98:99]
	v_add_f32_dpp v86, v86, v86 row_ror:8 row_mask:0xf bank_mask:0xf bound_ctrl:1
	v_mov_b32_e32 v87, v86
	v_lshl_add_u32 v147, v81, 10, v92
	global_load_dwordx4 v[62:65], v147, s[98:99]
	v_permlane16_swap_b32_e32 v86, v87
	v_add_f32_e32 v86, v86, v87
	v_mov_b32_e32 v87, v86
	ds_read_b32 v85, v90 offset:5632
	ds_read_b128 v[78:81], v91 offset:10752
	v_permlane32_swap_b32 v86, v87
	v_add_f32_e32 v86, v86, v87
	v_mul_f32_e32 v93, v88, v86
	s_mov_b64 exec, s[8:9]
	ds_write_b32 v89, v93 offset:10240
	s_mov_b64 exec, -1
	s_waitcnt vmcnt(12) lgkmcnt(10)
	s_add_i32 s10, s35, 1
	s_min_u32 s10, s10, 31
	s_sub_i32 s11, s35, 1
	s_max_i32 s11, s11, 0
	s_cmp_lg_u64 s[0:1], 0
	s_cselect_b32 s72, s10, s11
	s_lshl_b32 s36, s72, 4
	s_add_i32 s10, s93, s36
	v_mov_b32_e32 v91, s10
	v_mul_f32_e32 v88, v141, v82
	v_add_f32_dpp v200, v201, v200 quad_perm:[1,1,1,1] row_mask:0xf bank_mask:0xf bound_ctrl:1
	v_add_f32_dpp v202, v203, v202 quad_perm:[3,3,3,3] row_mask:0xf bank_mask:0xf bound_ctrl:1
	v_mfma_f32_16x16x32_fp8_fp8 v[184:187], v[2:3], v[122:123], 0
	v_add_f32_dpp v205, v204, v205 quad_perm:[0,0,0,0] row_mask:0xf bank_mask:0xf bound_ctrl:1
	v_add_f32_dpp v206, v207, v206 quad_perm:[3,3,3,3] row_mask:0xf bank_mask:0xf bound_ctrl:1
	v_mfma_f32_16x16x32_fp8_fp8 v[188:191], v[6:7], v[122:123], 0
	v_add_f32_dpp v230, v231, v230 quad_perm:[3,3,3,3] row_mask:0xf bank_mask:0xf bound_ctrl:1
	v_add_f32_dpp v228, v229, v228 quad_perm:[1,1,1,1] row_mask:0xf bank_mask:0xf bound_ctrl:1
	v_mfma_f32_16x16x32_fp8_fp8 v[192:195], v[10:11], v[122:123], 0
	v_add_f32_dpp v235, v234, v235 quad_perm:[2,2,2,2] row_mask:0xf bank_mask:0xf bound_ctrl:1
	v_add_f32_dpp v232, v233, v232 quad_perm:[1,1,1,1] row_mask:0xf bank_mask:0xf bound_ctrl:1
	v_mfma_f32_16x16x32_fp8_fp8 v[196:199], v[14:15], v[122:123], 0
	v_add_f32_dpp v200, v202, v200 quad_perm:[2,2,2,2] row_mask:0xf bank_mask:0xf bound_ctrl:1
	v_add_f32_dpp v205, v206, v205 quad_perm:[2,2,2,2] row_mask:0xf bank_mask:0xf bound_ctrl:1
	v_mfma_f32_16x16x32_fp8_fp8 v[184:187], v[4:5], v[124:125], v[184:187]
	v_add_f32_dpp v230, v228, v230 quad_perm:[0,0,0,0] row_mask:0xf bank_mask:0xf bound_ctrl:1
	v_add_f32_dpp v235, v232, v235 quad_perm:[0,0,0,0] row_mask:0xf bank_mask:0xf bound_ctrl:1
	v_mfma_f32_16x16x32_fp8_fp8 v[188:191], v[8:9], v[124:125], v[188:191]
	v_cndmask_b32_e64 v146, v205, v200, s[2:3]
	v_cndmask_b32_e64 v142, v235, v230, s[2:3]
	v_mfma_f32_16x16x32_fp8_fp8 v[192:195], v[12:13], v[124:125], v[192:195]
	v_cndmask_b32_e64 v86, v142, v146, s[4:5]
	v_mfma_f32_16x16x32_fp8_fp8 v[196:199], v[16:17], v[124:125], v[196:199]
	v_lshl_add_u32 v145, v66, 10, v92
	global_load_dwordx4 v[2:5], v145, s[98:99]
	v_cndmask_b32_e64 v86, 0, v86, s[6:7]
	v_lshl_add_u32 v147, v67, 10, v92
	global_load_dwordx4 v[6:9], v147, s[98:99]
	v_add_f32_dpp v86, v86, v86 row_ror:4 row_mask:0xf bank_mask:0xf bound_ctrl:1
	v_lshl_add_u32 v145, v68, 10, v92
	global_load_dwordx4 v[10:13], v145, s[98:99]
	v_add_f32_dpp v86, v86, v86 row_ror:8 row_mask:0xf bank_mask:0xf bound_ctrl:1
	v_mov_b32_e32 v87, v86
	v_lshl_add_u32 v147, v69, 10, v92
	global_load_dwordx4 v[14:17], v147, s[98:99]
	v_permlane16_swap_b32_e32 v86, v87
	v_add_f32_e32 v86, v86, v87
	v_mov_b32_e32 v87, v86
	ds_read_b32 v82, v90 offset:7168
	ds_read_b128 v[66:69], v91 offset:0
	v_permlane32_swap_b32 v86, v87
	v_add_f32_e32 v86, v86, v87
	v_mul_f32_e32 v93, v1, v86
	s_mov_b64 exec, s[8:9]
	ds_write_b32 v89, v93 offset:11776
	s_mov_b64 exec, -1
	v_mov_b32_e32 v89, v90
	v_add_u32_e32 v90, s36, v181
	s_mov_b32 s34, s35
	s_mov_b32 s35, s72
	s_add_i32 s95, s95, 1
	s_cmp_eq_u32 s95, 32
	s_cbranch_scc0 .Lus_loop
	s_waitcnt vmcnt(0) lgkmcnt(0)
	s_waitcnt lgkmcnt(0)
	s_waitcnt vmcnt(4)
	ds_read2st64_b32 v[2:3], v178 offset0:2 offset1:3
	ds_read2st64_b32 v[4:5], v178 offset0:4 offset1:5
	s_mov_b32 s0, 0x3e6d3388
	s_waitcnt lgkmcnt(0)
	v_fma_f32 v1, |v4|, s0, 1.0
	v_rcp_f32_e32 v1, v1
	v_cmp_gt_f32_e32 vcc, 0, v4
	v_fmamk_f32 v6, v1, 0x3f07dc22, v210
	v_fmaak_f32 v6, v1, v6, 0x3f35f0e3
	v_fmaak_f32 v6, v1, v6, 0xbe11a98e
	v_fmaak_f32 v6, v1, v6, 0x3e027906
	v_mul_f32_e32 v1, v1, v6
	v_mul_f32_e32 v6, v4, v4
	v_mul_f32_e32 v6, 0xbf38aa3b, v6
	v_exp_f32_e32 v6, v6
	s_nop 0
	v_mul_f32_e32 v1, v6, v1
	v_mul_f32_e32 v6, v4, v1
	v_fma_f32 v1, -v4, v1, v4
	v_cndmask_b32_e32 v1, v1, v6, vcc
	v_mul_f32_e32 v1, v2, v1
	v_fma_f32 v2, |v5|, s0, 1.0
	v_rcp_f32_e32 v2, v2
	v_cmp_gt_f32_e32 vcc, 0, v5
	v_fmamk_f32 v4, v2, 0x3f07dc22, v210
	v_fmaak_f32 v4, v2, v4, 0x3f35f0e3
	v_fmaak_f32 v4, v2, v4, 0xbe11a98e
	v_fmaak_f32 v4, v2, v4, 0x3e027906
	v_mul_f32_e32 v2, v2, v4
	v_mul_f32_e32 v4, v5, v5
	v_mul_f32_e32 v4, 0xbf38aa3b, v4
	v_exp_f32_e32 v4, v4
	s_nop 0
	v_mul_f32_e32 v2, v4, v2
	v_mul_f32_e32 v4, v5, v2
	v_fma_f32 v2, -v5, v2, v5
	v_cndmask_b32_e32 v2, v2, v4, vcc
	v_mul_f32_e32 v2, v3, v2
	v_max_f32_e64 v3, |v1|, |v2|
	s_nop 1
	v_mov_b32_dpp v4, v3 quad_perm:[1,0,3,2] row_mask:0xf bank_mask:0xf bound_ctrl:1
	v_max_f32_e32 v4, v4, v4
	v_max_f32_e32 v3, v3, v4
	s_nop 1
	v_mov_b32_dpp v4, v3 quad_perm:[2,3,0,1] row_mask:0xf bank_mask:0xf bound_ctrl:1
	v_max_f32_e32 v4, v4, v4
	v_max_f32_e32 v3, v3, v4
	s_nop 1
	v_mov_b32_dpp v4, v3 row_half_mirror row_mask:0xf bank_mask:0xf bound_ctrl:1
	v_max_f32_e32 v4, v4, v4
	v_max_f32_e32 v3, v3, v4
	s_nop 1
	v_mov_b32_dpp v4, v3 row_mirror row_mask:0xf bank_mask:0xf bound_ctrl:1
	v_max_f32_e32 v4, v4, v4
	v_max_f32_e32 v3, v3, v4
	s_nop 0
	v_readlane_b32 s0, v3, 0
	v_readlane_b32 s1, v3, 16
	v_readlane_b32 s10, v3, 32
	v_readlane_b32 s11, v3, 48
	v_max_f32_e64 v3, s1, s1
	v_max_f32_e64 v4, s0, s0
	v_max_f32_e32 v3, v4, v3
	v_max_f32_e64 v4, s11, s11
	v_max_f32_e64 v5, s10, s10
	v_max_f32_e32 v4, v5, v4
	s_mov_b32 s0, 0xda24260
	v_max3_f32 v3, v3, v4, s0
	s_mov_b64 s[0:1], exec
	v_readlane_b32 s10, v254, 21
	v_readlane_b32 s11, v254, 22
	s_and_b64 s[10:11], s[0:1], s[10:11]
	s_mov_b64 exec, s[10:11]
	v_mul_f32_e32 v4, 0x3b888889, v3
	v_mov_b32_e32 v5, s93
	ds_write_b32 v5, v4 offset:14336
	s_or_b64 exec, exec, s[0:1]
	s_mov_b32 s10, 0x43700000
	v_div_scale_f32 v4, s[0:1], v3, v3, s10
	v_rcp_f32_e32 v5, v4
	s_mov_b32 s0, 0x7020c0c
	v_fma_f32 v6, -v4, v5, 1.0
	v_fmac_f32_e32 v5, v6, v5
	v_div_scale_f32 v6, vcc, s10, v3, s10
	v_mul_f32_e32 v7, v6, v5
	v_fma_f32 v8, -v4, v7, v6
	v_fmac_f32_e32 v7, v8, v5
	v_fma_f32 v4, -v4, v7, v6
	v_div_fmas_f32 v4, v4, v5, v7
	v_div_fixup_f32 v3, v4, v3, s10
	v_mul_f32_e32 v4, v3, v1
	v_mul_f32_e32 v5, v3, v2
	v_mov_b32_e32 v6, v155
	v_cvt_pk_fp8_f32 v6, v4, v5
	v_cvt_pk_f32_fp8_e32 v[4:5], v6
	v_fma_f32 v1, v3, v1, -v4
	v_fma_f32 v2, v3, v2, -v5
	v_mov_b32_e32 v4, v155
	v_cvt_pk_fp8_f32 v4, v1, v2
	ds_read2st64_b32 v[2:3], v178 offset1:1
	v_lshlrev_b32_e32 v1, 16, v6
	v_and_b32_e32 v1, 0xff0000, v1
	v_lshlrev_b32_e32 v5, 24, v4
	v_lshlrev_b32_e32 v4, 16, v4
	s_waitcnt lgkmcnt(0)
	v_or3_b32 v1, v2, v1, v5
	v_lshlrev_b32_e32 v2, 8, v6
	v_perm_b32 v2, v4, v2, s0
	v_or_b32_e32 v2, v2, v3
	ds_write2st64_b32 v178, v1, v2 offset0:2 offset1:3
	ds_read2st64_b32 v[2:3], v178 offset0:8 offset1:9
	ds_read2st64_b32 v[4:5], v178 offset0:10 offset1:11
	s_mov_b32 s0, 0x3e6d3388
	s_waitcnt lgkmcnt(0)
	v_fma_f32 v1, |v4|, s0, 1.0
	v_rcp_f32_e32 v1, v1
	v_cmp_gt_f32_e32 vcc, 0, v4
	v_fmamk_f32 v6, v1, 0x3f07dc22, v210
	v_fmaak_f32 v6, v1, v6, 0x3f35f0e3
	v_fmaak_f32 v6, v1, v6, 0xbe11a98e
	v_fmaak_f32 v6, v1, v6, 0x3e027906
	v_mul_f32_e32 v1, v1, v6
	v_mul_f32_e32 v6, v4, v4
	v_mul_f32_e32 v6, 0xbf38aa3b, v6
	v_exp_f32_e32 v6, v6
	s_nop 0
	v_mul_f32_e32 v1, v6, v1
	v_mul_f32_e32 v6, v4, v1
	v_fma_f32 v1, -v4, v1, v4
	v_cndmask_b32_e32 v1, v1, v6, vcc
	v_mul_f32_e32 v1, v2, v1
	v_fma_f32 v2, |v5|, s0, 1.0
	v_rcp_f32_e32 v2, v2
	v_cmp_gt_f32_e32 vcc, 0, v5
	v_fmamk_f32 v4, v2, 0x3f07dc22, v210
	v_fmaak_f32 v4, v2, v4, 0x3f35f0e3
	v_fmaak_f32 v4, v2, v4, 0xbe11a98e
	v_fmaak_f32 v4, v2, v4, 0x3e027906
	v_mul_f32_e32 v2, v2, v4
	v_mul_f32_e32 v4, v5, v5
	v_mul_f32_e32 v4, 0xbf38aa3b, v4
	v_exp_f32_e32 v4, v4
	s_nop 0
	v_mul_f32_e32 v2, v4, v2
	v_mul_f32_e32 v4, v5, v2
	v_fma_f32 v2, -v5, v2, v5
	v_cndmask_b32_e32 v2, v2, v4, vcc
	v_mul_f32_e32 v2, v3, v2
	v_max_f32_e64 v3, |v1|, |v2|
	s_nop 1
	v_mov_b32_dpp v4, v3 quad_perm:[1,0,3,2] row_mask:0xf bank_mask:0xf bound_ctrl:1
	v_max_f32_e32 v4, v4, v4
	v_max_f32_e32 v3, v3, v4
	s_nop 1
	v_mov_b32_dpp v4, v3 quad_perm:[2,3,0,1] row_mask:0xf bank_mask:0xf bound_ctrl:1
	v_max_f32_e32 v4, v4, v4
	v_max_f32_e32 v3, v3, v4
	s_nop 1
	v_mov_b32_dpp v4, v3 row_half_mirror row_mask:0xf bank_mask:0xf bound_ctrl:1
	v_max_f32_e32 v4, v4, v4
	v_max_f32_e32 v3, v3, v4
	s_nop 1
	v_mov_b32_dpp v4, v3 row_mirror row_mask:0xf bank_mask:0xf bound_ctrl:1
	v_max_f32_e32 v4, v4, v4
	v_max_f32_e32 v3, v3, v4
	s_nop 0
	v_readlane_b32 s0, v3, 0
	v_readlane_b32 s1, v3, 16
	v_readlane_b32 s10, v3, 32
	v_readlane_b32 s11, v3, 48
	v_max_f32_e64 v3, s1, s1
	v_max_f32_e64 v4, s0, s0
	v_max_f32_e32 v3, v4, v3
	v_max_f32_e64 v4, s11, s11
	v_max_f32_e64 v5, s10, s10
	v_max_f32_e32 v4, v5, v4
	s_mov_b32 s0, 0xda24260
	v_max3_f32 v3, v3, v4, s0
	s_mov_b64 s[0:1], exec
	v_readlane_b32 s10, v254, 21
	v_readlane_b32 s11, v254, 22
	s_and_b64 s[10:11], s[0:1], s[10:11]
	s_mov_b64 exec, s[10:11]
	v_mul_f32_e32 v4, 0x3b888889, v3
	v_mov_b32_e32 v5, s93
	ds_write_b32 v5, v4 offset:14340
	s_or_b64 exec, exec, s[0:1]
	s_mov_b32 s10, 0x43700000
	v_div_scale_f32 v4, s[0:1], v3, v3, s10
	v_rcp_f32_e32 v5, v4
	s_mov_b32 s0, 0x7020c0c
	v_fma_f32 v6, -v4, v5, 1.0
	v_fmac_f32_e32 v5, v6, v5
	v_div_scale_f32 v6, vcc, s10, v3, s10
	v_mul_f32_e32 v7, v6, v5
	v_fma_f32 v8, -v4, v7, v6
	v_fmac_f32_e32 v7, v8, v5
	v_fma_f32 v4, -v4, v7, v6
	v_div_fmas_f32 v4, v4, v5, v7
	v_div_fixup_f32 v3, v4, v3, s10
	v_mul_f32_e32 v4, v3, v1
	v_mul_f32_e32 v5, v3, v2
	v_mov_b32_e32 v6, v155
	v_cvt_pk_fp8_f32 v6, v4, v5
	v_cvt_pk_f32_fp8_e32 v[4:5], v6
	v_fma_f32 v1, v3, v1, -v4
	v_fma_f32 v2, v3, v2, -v5
	v_mov_b32_e32 v4, v155
	v_cvt_pk_fp8_f32 v4, v1, v2
	ds_read2st64_b32 v[2:3], v178 offset0:6 offset1:7
	v_lshlrev_b32_e32 v1, 16, v6
	v_and_b32_e32 v1, 0xff0000, v1
	v_lshlrev_b32_e32 v5, 24, v4
	v_lshlrev_b32_e32 v4, 16, v4
	s_waitcnt lgkmcnt(0)
	v_or3_b32 v1, v2, v1, v5
	v_lshlrev_b32_e32 v2, 8, v6
	v_perm_b32 v2, v4, v2, s0
	v_or_b32_e32 v2, v2, v3
	ds_write2st64_b32 v178, v1, v2 offset0:8 offset1:9
	ds_read2st64_b32 v[2:3], v178 offset0:14 offset1:15
	ds_read2st64_b32 v[4:5], v178 offset0:16 offset1:17
	s_mov_b32 s0, 0x3e6d3388
	s_waitcnt lgkmcnt(0)
	v_fma_f32 v1, |v4|, s0, 1.0
	v_rcp_f32_e32 v1, v1
	v_cmp_gt_f32_e32 vcc, 0, v4
	v_fmamk_f32 v6, v1, 0x3f07dc22, v210
	v_fmaak_f32 v6, v1, v6, 0x3f35f0e3
	v_fmaak_f32 v6, v1, v6, 0xbe11a98e
	v_fmaak_f32 v6, v1, v6, 0x3e027906
	v_mul_f32_e32 v1, v1, v6
	v_mul_f32_e32 v6, v4, v4
	v_mul_f32_e32 v6, 0xbf38aa3b, v6
	v_exp_f32_e32 v6, v6
	s_nop 0
	v_mul_f32_e32 v1, v6, v1
	v_mul_f32_e32 v6, v4, v1
	v_fma_f32 v1, -v4, v1, v4
	v_cndmask_b32_e32 v1, v1, v6, vcc
	v_mul_f32_e32 v1, v2, v1
	v_fma_f32 v2, |v5|, s0, 1.0
	v_rcp_f32_e32 v2, v2
	v_cmp_gt_f32_e32 vcc, 0, v5
	v_fmamk_f32 v4, v2, 0x3f07dc22, v210
	v_fmaak_f32 v4, v2, v4, 0x3f35f0e3
	v_fmaak_f32 v4, v2, v4, 0xbe11a98e
	v_fmaak_f32 v4, v2, v4, 0x3e027906
	v_mul_f32_e32 v2, v2, v4
	v_mul_f32_e32 v4, v5, v5
	v_mul_f32_e32 v4, 0xbf38aa3b, v4
	v_exp_f32_e32 v4, v4
	s_nop 0
	v_mul_f32_e32 v2, v4, v2
	v_mul_f32_e32 v4, v5, v2
	v_fma_f32 v2, -v5, v2, v5
	v_cndmask_b32_e32 v2, v2, v4, vcc
	v_mul_f32_e32 v2, v3, v2
	v_max_f32_e64 v3, |v1|, |v2|
	s_nop 1
	v_mov_b32_dpp v4, v3 quad_perm:[1,0,3,2] row_mask:0xf bank_mask:0xf bound_ctrl:1
	v_max_f32_e32 v4, v4, v4
	v_max_f32_e32 v3, v3, v4
	s_nop 1
	v_mov_b32_dpp v4, v3 quad_perm:[2,3,0,1] row_mask:0xf bank_mask:0xf bound_ctrl:1
	v_max_f32_e32 v4, v4, v4
	v_max_f32_e32 v3, v3, v4
	s_nop 1
	v_mov_b32_dpp v4, v3 row_half_mirror row_mask:0xf bank_mask:0xf bound_ctrl:1
	v_max_f32_e32 v4, v4, v4
	v_max_f32_e32 v3, v3, v4
	s_nop 1
	v_mov_b32_dpp v4, v3 row_mirror row_mask:0xf bank_mask:0xf bound_ctrl:1
	v_max_f32_e32 v4, v4, v4
	v_max_f32_e32 v3, v3, v4
	s_nop 0
	v_readlane_b32 s0, v3, 0
	v_readlane_b32 s1, v3, 16
	v_readlane_b32 s10, v3, 32
	v_readlane_b32 s11, v3, 48
	v_max_f32_e64 v3, s1, s1
	v_max_f32_e64 v4, s0, s0
	v_max_f32_e32 v3, v4, v3
	v_max_f32_e64 v4, s11, s11
	v_max_f32_e64 v5, s10, s10
	v_max_f32_e32 v4, v5, v4
	s_mov_b32 s0, 0xda24260
	v_max3_f32 v3, v3, v4, s0
	s_mov_b64 s[0:1], exec
	v_readlane_b32 s10, v254, 21
	v_readlane_b32 s11, v254, 22
	s_and_b64 s[10:11], s[0:1], s[10:11]
	s_mov_b64 exec, s[10:11]
	v_mul_f32_e32 v4, 0x3b888889, v3
	v_mov_b32_e32 v5, s93
	ds_write_b32 v5, v4 offset:14344
	s_or_b64 exec, exec, s[0:1]
	s_mov_b32 s10, 0x43700000
	v_div_scale_f32 v4, s[0:1], v3, v3, s10
	v_rcp_f32_e32 v5, v4
	s_mov_b32 s0, 0x7020c0c
	v_fma_f32 v6, -v4, v5, 1.0
	v_fmac_f32_e32 v5, v6, v5
	v_div_scale_f32 v6, vcc, s10, v3, s10
	v_mul_f32_e32 v7, v6, v5
	v_fma_f32 v8, -v4, v7, v6
	v_fmac_f32_e32 v7, v8, v5
	v_fma_f32 v4, -v4, v7, v6
	v_div_fmas_f32 v4, v4, v5, v7
	v_div_fixup_f32 v3, v4, v3, s10
	v_mul_f32_e32 v4, v3, v1
	v_mul_f32_e32 v5, v3, v2
	v_mov_b32_e32 v6, v155
	v_cvt_pk_fp8_f32 v6, v4, v5
	v_cvt_pk_f32_fp8_e32 v[4:5], v6
	v_fma_f32 v1, v3, v1, -v4
	v_fma_f32 v2, v3, v2, -v5
	v_mov_b32_e32 v4, v155
	v_cvt_pk_fp8_f32 v4, v1, v2
	ds_read2st64_b32 v[2:3], v178 offset0:12 offset1:13
	v_lshlrev_b32_e32 v1, 16, v6
	v_and_b32_e32 v1, 0xff0000, v1
	v_lshlrev_b32_e32 v5, 24, v4
	v_lshlrev_b32_e32 v4, 16, v4
	s_waitcnt lgkmcnt(0)
	v_or3_b32 v1, v2, v1, v5
	v_lshlrev_b32_e32 v2, 8, v6
	v_perm_b32 v2, v4, v2, s0
	v_or_b32_e32 v2, v2, v3
	ds_write2st64_b32 v178, v1, v2 offset0:14 offset1:15
	ds_read2st64_b32 v[2:3], v178 offset0:20 offset1:21
	ds_read2st64_b32 v[4:5], v178 offset0:22 offset1:23
	s_mov_b32 s0, 0x3e6d3388
	s_waitcnt lgkmcnt(0)
	v_fma_f32 v1, |v4|, s0, 1.0
	v_rcp_f32_e32 v1, v1
	v_cmp_gt_f32_e32 vcc, 0, v4
	v_fmamk_f32 v6, v1, 0x3f07dc22, v210
	v_fmaak_f32 v6, v1, v6, 0x3f35f0e3
	v_fmaak_f32 v6, v1, v6, 0xbe11a98e
	v_fmaak_f32 v6, v1, v6, 0x3e027906
	v_mul_f32_e32 v1, v1, v6
	v_mul_f32_e32 v6, v4, v4
	v_mul_f32_e32 v6, 0xbf38aa3b, v6
	v_exp_f32_e32 v6, v6
	s_nop 0
	v_mul_f32_e32 v1, v6, v1
	v_mul_f32_e32 v6, v4, v1
	v_fma_f32 v1, -v4, v1, v4
	v_cndmask_b32_e32 v1, v1, v6, vcc
	v_mul_f32_e32 v1, v2, v1
	v_fma_f32 v2, |v5|, s0, 1.0
	v_rcp_f32_e32 v2, v2
	v_cmp_gt_f32_e32 vcc, 0, v5
	v_fmamk_f32 v4, v2, 0x3f07dc22, v210
	v_fmaak_f32 v4, v2, v4, 0x3f35f0e3
	v_fmaak_f32 v4, v2, v4, 0xbe11a98e
	v_fmaak_f32 v4, v2, v4, 0x3e027906
	v_mul_f32_e32 v2, v2, v4
	v_mul_f32_e32 v4, v5, v5
	v_mul_f32_e32 v4, 0xbf38aa3b, v4
	v_exp_f32_e32 v4, v4
	s_nop 0
	v_mul_f32_e32 v2, v4, v2
	v_mul_f32_e32 v4, v5, v2
	v_fma_f32 v2, -v5, v2, v5
	v_cndmask_b32_e32 v2, v2, v4, vcc
	v_mul_f32_e32 v2, v3, v2
	v_max_f32_e64 v3, |v1|, |v2|
	s_nop 1
	v_mov_b32_dpp v4, v3 quad_perm:[1,0,3,2] row_mask:0xf bank_mask:0xf bound_ctrl:1
	v_max_f32_e32 v4, v4, v4
	v_max_f32_e32 v3, v3, v4
	s_nop 1
	v_mov_b32_dpp v4, v3 quad_perm:[2,3,0,1] row_mask:0xf bank_mask:0xf bound_ctrl:1
	v_max_f32_e32 v4, v4, v4
	v_max_f32_e32 v3, v3, v4
	s_nop 1
	v_mov_b32_dpp v4, v3 row_half_mirror row_mask:0xf bank_mask:0xf bound_ctrl:1
	v_max_f32_e32 v4, v4, v4
	v_max_f32_e32 v3, v3, v4
	s_nop 1
	v_mov_b32_dpp v4, v3 row_mirror row_mask:0xf bank_mask:0xf bound_ctrl:1
	v_max_f32_e32 v4, v4, v4
	v_max_f32_e32 v3, v3, v4
	s_nop 0
	v_readlane_b32 s0, v3, 0
	v_readlane_b32 s1, v3, 16
	v_readlane_b32 s10, v3, 32
	v_readlane_b32 s11, v3, 48
	v_max_f32_e64 v3, s1, s1
	v_max_f32_e64 v4, s0, s0
	v_max_f32_e32 v3, v4, v3
	v_max_f32_e64 v4, s11, s11
	v_max_f32_e64 v5, s10, s10
	v_max_f32_e32 v4, v5, v4
	s_mov_b32 s0, 0xda24260
	v_max3_f32 v3, v3, v4, s0
	s_mov_b64 s[0:1], exec
	v_readlane_b32 s10, v254, 21
	v_readlane_b32 s11, v254, 22
	s_and_b64 s[10:11], s[0:1], s[10:11]
	s_mov_b64 exec, s[10:11]
	v_mul_f32_e32 v4, 0x3b888889, v3
	v_mov_b32_e32 v5, s93
	ds_write_b32 v5, v4 offset:14348
	s_or_b64 exec, exec, s[0:1]
	s_mov_b32 s10, 0x43700000
	v_div_scale_f32 v4, s[0:1], v3, v3, s10
	v_rcp_f32_e32 v5, v4
	s_mov_b32 s0, 0x7020c0c
	v_fma_f32 v6, -v4, v5, 1.0
	v_fmac_f32_e32 v5, v6, v5
	v_div_scale_f32 v6, vcc, s10, v3, s10
	v_mul_f32_e32 v7, v6, v5
	v_fma_f32 v8, -v4, v7, v6
	v_fmac_f32_e32 v7, v8, v5
	v_fma_f32 v4, -v4, v7, v6
	v_div_fmas_f32 v4, v4, v5, v7
	v_div_fixup_f32 v3, v4, v3, s10
	v_mul_f32_e32 v4, v3, v1
	v_mul_f32_e32 v5, v3, v2
	v_mov_b32_e32 v6, v155
	v_cvt_pk_fp8_f32 v6, v4, v5
	v_cvt_pk_f32_fp8_e32 v[4:5], v6
	v_fma_f32 v1, v3, v1, -v4
	v_fma_f32 v2, v3, v2, -v5
	v_mov_b32_e32 v4, v155
	v_cvt_pk_fp8_f32 v4, v1, v2
	ds_read2st64_b32 v[2:3], v178 offset0:18 offset1:19
	v_lshlrev_b32_e32 v1, 16, v6
	v_and_b32_e32 v1, 0xff0000, v1
	v_lshlrev_b32_e32 v5, 24, v4
	v_lshlrev_b32_e32 v4, 16, v4
	s_waitcnt lgkmcnt(0)
	v_or3_b32 v1, v2, v1, v5
	v_lshlrev_b32_e32 v2, 8, v6
	v_perm_b32 v2, v4, v2, s0
	v_or_b32_e32 v2, v2, v3
	ds_write2st64_b32 v178, v1, v2 offset0:20 offset1:21
	ds_read2st64_b32 v[2:3], v178 offset0:26 offset1:27
	ds_read2st64_b32 v[4:5], v178 offset0:28 offset1:29
	s_mov_b32 s0, 0x3e6d3388
	s_waitcnt lgkmcnt(0)
	v_fma_f32 v1, |v4|, s0, 1.0
	v_rcp_f32_e32 v1, v1
	v_cmp_gt_f32_e32 vcc, 0, v4
	v_fmamk_f32 v6, v1, 0x3f07dc22, v210
	v_fmaak_f32 v6, v1, v6, 0x3f35f0e3
	v_fmaak_f32 v6, v1, v6, 0xbe11a98e
	v_fmaak_f32 v6, v1, v6, 0x3e027906
	v_mul_f32_e32 v1, v1, v6
	v_mul_f32_e32 v6, v4, v4
	v_mul_f32_e32 v6, 0xbf38aa3b, v6
	v_exp_f32_e32 v6, v6
	s_nop 0
	v_mul_f32_e32 v1, v6, v1
	v_mul_f32_e32 v6, v4, v1
	v_fma_f32 v1, -v4, v1, v4
	v_cndmask_b32_e32 v1, v1, v6, vcc
	v_mul_f32_e32 v1, v2, v1
	v_fma_f32 v2, |v5|, s0, 1.0
	v_rcp_f32_e32 v2, v2
	v_cmp_gt_f32_e32 vcc, 0, v5
	v_fmamk_f32 v4, v2, 0x3f07dc22, v210
	v_fmaak_f32 v4, v2, v4, 0x3f35f0e3
	v_fmaak_f32 v4, v2, v4, 0xbe11a98e
	v_fmaak_f32 v4, v2, v4, 0x3e027906
	v_mul_f32_e32 v2, v2, v4
	v_mul_f32_e32 v4, v5, v5
	v_mul_f32_e32 v4, 0xbf38aa3b, v4
	v_exp_f32_e32 v4, v4
	s_nop 0
	v_mul_f32_e32 v2, v4, v2
	v_mul_f32_e32 v4, v5, v2
	v_fma_f32 v2, -v5, v2, v5
	v_cndmask_b32_e32 v2, v2, v4, vcc
	v_mul_f32_e32 v2, v3, v2
	v_max_f32_e64 v3, |v1|, |v2|
	s_nop 1
	v_mov_b32_dpp v4, v3 quad_perm:[1,0,3,2] row_mask:0xf bank_mask:0xf bound_ctrl:1
	v_max_f32_e32 v4, v4, v4
	v_max_f32_e32 v3, v3, v4
	s_nop 1
	v_mov_b32_dpp v4, v3 quad_perm:[2,3,0,1] row_mask:0xf bank_mask:0xf bound_ctrl:1
	v_max_f32_e32 v4, v4, v4
	v_max_f32_e32 v3, v3, v4
	s_nop 1
	v_mov_b32_dpp v4, v3 row_half_mirror row_mask:0xf bank_mask:0xf bound_ctrl:1
	v_max_f32_e32 v4, v4, v4
	v_max_f32_e32 v3, v3, v4
	s_nop 1
	v_mov_b32_dpp v4, v3 row_mirror row_mask:0xf bank_mask:0xf bound_ctrl:1
	v_max_f32_e32 v4, v4, v4
	v_max_f32_e32 v3, v3, v4
	s_nop 0
	v_readlane_b32 s0, v3, 0
	v_readlane_b32 s1, v3, 16
	v_readlane_b32 s10, v3, 32
	v_readlane_b32 s11, v3, 48
	v_max_f32_e64 v3, s1, s1
	v_max_f32_e64 v4, s0, s0
	v_max_f32_e32 v3, v4, v3
	v_max_f32_e64 v4, s11, s11
	v_max_f32_e64 v5, s10, s10
	v_max_f32_e32 v4, v5, v4
	s_mov_b32 s0, 0xda24260
	v_max3_f32 v3, v3, v4, s0
	s_mov_b64 s[0:1], exec
	v_readlane_b32 s10, v254, 21
	v_readlane_b32 s11, v254, 22
	s_and_b64 s[10:11], s[0:1], s[10:11]
	s_mov_b64 exec, s[10:11]
	v_mul_f32_e32 v4, 0x3b888889, v3
	v_mov_b32_e32 v5, s93
	ds_write_b32 v5, v4 offset:14352
	s_or_b64 exec, exec, s[0:1]
	s_mov_b32 s10, 0x43700000
	v_div_scale_f32 v4, s[0:1], v3, v3, s10
	v_rcp_f32_e32 v5, v4
	s_mov_b32 s0, 0x7020c0c
	v_fma_f32 v6, -v4, v5, 1.0
	v_fmac_f32_e32 v5, v6, v5
	v_div_scale_f32 v6, vcc, s10, v3, s10
	v_mul_f32_e32 v7, v6, v5
	v_fma_f32 v8, -v4, v7, v6
	v_fmac_f32_e32 v7, v8, v5
	v_fma_f32 v4, -v4, v7, v6
	v_div_fmas_f32 v4, v4, v5, v7
	v_div_fixup_f32 v3, v4, v3, s10
	v_mul_f32_e32 v4, v3, v1
	v_mul_f32_e32 v5, v3, v2
	v_mov_b32_e32 v6, v155
	v_cvt_pk_fp8_f32 v6, v4, v5
	v_cvt_pk_f32_fp8_e32 v[4:5], v6
	v_fma_f32 v1, v3, v1, -v4
	v_fma_f32 v2, v3, v2, -v5
	v_mov_b32_e32 v4, v155
	v_cvt_pk_fp8_f32 v4, v1, v2
	ds_read2st64_b32 v[2:3], v178 offset0:24 offset1:25
	v_lshlrev_b32_e32 v1, 16, v6
	v_and_b32_e32 v1, 0xff0000, v1
	v_lshlrev_b32_e32 v5, 24, v4
	v_lshlrev_b32_e32 v4, 16, v4
	s_waitcnt lgkmcnt(0)
	v_or3_b32 v1, v2, v1, v5
	v_lshlrev_b32_e32 v2, 8, v6
	v_perm_b32 v2, v4, v2, s0
	v_or_b32_e32 v2, v2, v3
	ds_write2st64_b32 v178, v1, v2 offset0:26 offset1:27
	ds_read2st64_b32 v[2:3], v178 offset0:32 offset1:33
	ds_read2st64_b32 v[4:5], v178 offset0:34 offset1:35
	s_mov_b32 s0, 0x3e6d3388
	s_waitcnt lgkmcnt(0)
	v_fma_f32 v1, |v4|, s0, 1.0
	v_rcp_f32_e32 v1, v1
	v_cmp_gt_f32_e32 vcc, 0, v4
	v_fmamk_f32 v6, v1, 0x3f07dc22, v210
	v_fmaak_f32 v6, v1, v6, 0x3f35f0e3
	v_fmaak_f32 v6, v1, v6, 0xbe11a98e
	v_fmaak_f32 v6, v1, v6, 0x3e027906
	v_mul_f32_e32 v1, v1, v6
	v_mul_f32_e32 v6, v4, v4
	v_mul_f32_e32 v6, 0xbf38aa3b, v6
	v_exp_f32_e32 v6, v6
	s_nop 0
	v_mul_f32_e32 v1, v6, v1
	v_mul_f32_e32 v6, v4, v1
	v_fma_f32 v1, -v4, v1, v4
	v_cndmask_b32_e32 v1, v1, v6, vcc
	v_mul_f32_e32 v1, v2, v1
	v_fma_f32 v2, |v5|, s0, 1.0
	v_rcp_f32_e32 v2, v2
	v_cmp_gt_f32_e32 vcc, 0, v5
	v_fmamk_f32 v4, v2, 0x3f07dc22, v210
	v_fmaak_f32 v4, v2, v4, 0x3f35f0e3
	v_fmaak_f32 v4, v2, v4, 0xbe11a98e
	v_fmaak_f32 v4, v2, v4, 0x3e027906
	v_mul_f32_e32 v2, v2, v4
	v_mul_f32_e32 v4, v5, v5
	v_mul_f32_e32 v4, 0xbf38aa3b, v4
	v_exp_f32_e32 v4, v4
	s_nop 0
	v_mul_f32_e32 v2, v4, v2
	v_mul_f32_e32 v4, v5, v2
	v_fma_f32 v2, -v5, v2, v5
	v_cndmask_b32_e32 v2, v2, v4, vcc
	v_mul_f32_e32 v2, v3, v2
	v_max_f32_e64 v3, |v1|, |v2|
	s_nop 1
	v_mov_b32_dpp v4, v3 quad_perm:[1,0,3,2] row_mask:0xf bank_mask:0xf bound_ctrl:1
	v_max_f32_e32 v4, v4, v4
	v_max_f32_e32 v3, v3, v4
	s_nop 1
	v_mov_b32_dpp v4, v3 quad_perm:[2,3,0,1] row_mask:0xf bank_mask:0xf bound_ctrl:1
	v_max_f32_e32 v4, v4, v4
	v_max_f32_e32 v3, v3, v4
	s_nop 1
	v_mov_b32_dpp v4, v3 row_half_mirror row_mask:0xf bank_mask:0xf bound_ctrl:1
	v_max_f32_e32 v4, v4, v4
	v_max_f32_e32 v3, v3, v4
	s_nop 1
	v_mov_b32_dpp v4, v3 row_mirror row_mask:0xf bank_mask:0xf bound_ctrl:1
	v_max_f32_e32 v4, v4, v4
	v_max_f32_e32 v3, v3, v4
	s_nop 0
	v_readlane_b32 s0, v3, 0
	v_readlane_b32 s1, v3, 16
	v_readlane_b32 s10, v3, 32
	v_readlane_b32 s11, v3, 48
	v_max_f32_e64 v3, s1, s1
	v_max_f32_e64 v4, s0, s0
	v_max_f32_e32 v3, v4, v3
	v_max_f32_e64 v4, s11, s11
	v_max_f32_e64 v5, s10, s10
	v_max_f32_e32 v4, v5, v4
	s_mov_b32 s0, 0xda24260
	v_max3_f32 v3, v3, v4, s0
	s_mov_b64 s[0:1], exec
	v_readlane_b32 s10, v254, 21
	v_readlane_b32 s11, v254, 22
	s_and_b64 s[10:11], s[0:1], s[10:11]
	s_mov_b64 exec, s[10:11]
	v_mul_f32_e32 v4, 0x3b888889, v3
	v_mov_b32_e32 v5, s93
	ds_write_b32 v5, v4 offset:14356
	s_or_b64 exec, exec, s[0:1]
	s_mov_b32 s10, 0x43700000
	v_div_scale_f32 v4, s[0:1], v3, v3, s10
	v_rcp_f32_e32 v5, v4
	s_mov_b32 s0, 0x7020c0c
	v_fma_f32 v6, -v4, v5, 1.0
	v_fmac_f32_e32 v5, v6, v5
	v_div_scale_f32 v6, vcc, s10, v3, s10
	v_mul_f32_e32 v7, v6, v5
	v_fma_f32 v8, -v4, v7, v6
	v_fmac_f32_e32 v7, v8, v5
	v_fma_f32 v4, -v4, v7, v6
	v_div_fmas_f32 v4, v4, v5, v7
	v_div_fixup_f32 v3, v4, v3, s10
	v_mul_f32_e32 v4, v3, v1
	v_mul_f32_e32 v5, v3, v2
	v_mov_b32_e32 v6, v155
	v_cvt_pk_fp8_f32 v6, v4, v5
	v_cvt_pk_f32_fp8_e32 v[4:5], v6
	v_fma_f32 v1, v3, v1, -v4
	v_fma_f32 v2, v3, v2, -v5
	v_mov_b32_e32 v4, v155
	v_cvt_pk_fp8_f32 v4, v1, v2
	ds_read2st64_b32 v[2:3], v178 offset0:30 offset1:31
	v_lshlrev_b32_e32 v1, 16, v6
	v_and_b32_e32 v1, 0xff0000, v1
	v_lshlrev_b32_e32 v5, 24, v4
	v_lshlrev_b32_e32 v4, 16, v4
	s_waitcnt lgkmcnt(0)
	v_or3_b32 v1, v2, v1, v5
	v_lshlrev_b32_e32 v2, 8, v6
	v_perm_b32 v2, v4, v2, s0
	v_or_b32_e32 v2, v2, v3
	ds_write2st64_b32 v178, v1, v2 offset0:32 offset1:33
	ds_read2st64_b32 v[2:3], v178 offset0:38 offset1:39
	ds_read2st64_b32 v[4:5], v178 offset0:40 offset1:41
	s_mov_b32 s0, 0x3e6d3388
	s_waitcnt lgkmcnt(0)
	v_fma_f32 v1, |v4|, s0, 1.0
	v_rcp_f32_e32 v1, v1
	v_cmp_gt_f32_e32 vcc, 0, v4
	v_fmamk_f32 v6, v1, 0x3f07dc22, v210
	v_fmaak_f32 v6, v1, v6, 0x3f35f0e3
	v_fmaak_f32 v6, v1, v6, 0xbe11a98e
	v_fmaak_f32 v6, v1, v6, 0x3e027906
	v_mul_f32_e32 v1, v1, v6
	v_mul_f32_e32 v6, v4, v4
	v_mul_f32_e32 v6, 0xbf38aa3b, v6
	v_exp_f32_e32 v6, v6
	s_nop 0
	v_mul_f32_e32 v1, v6, v1
	v_mul_f32_e32 v6, v4, v1
	v_fma_f32 v1, -v4, v1, v4
	v_cndmask_b32_e32 v1, v1, v6, vcc
	v_mul_f32_e32 v1, v2, v1
	v_fma_f32 v2, |v5|, s0, 1.0
	v_rcp_f32_e32 v2, v2
	v_cmp_gt_f32_e32 vcc, 0, v5
	v_fmamk_f32 v4, v2, 0x3f07dc22, v210
	v_fmaak_f32 v4, v2, v4, 0x3f35f0e3
	v_fmaak_f32 v4, v2, v4, 0xbe11a98e
	v_fmaak_f32 v4, v2, v4, 0x3e027906
	v_mul_f32_e32 v2, v2, v4
	v_mul_f32_e32 v4, v5, v5
	v_mul_f32_e32 v4, 0xbf38aa3b, v4
	v_exp_f32_e32 v4, v4
	s_nop 0
	v_mul_f32_e32 v2, v4, v2
	v_mul_f32_e32 v4, v5, v2
	v_fma_f32 v2, -v5, v2, v5
	v_cndmask_b32_e32 v2, v2, v4, vcc
	v_mul_f32_e32 v2, v3, v2
	v_max_f32_e64 v3, |v1|, |v2|
	s_nop 1
	v_mov_b32_dpp v4, v3 quad_perm:[1,0,3,2] row_mask:0xf bank_mask:0xf bound_ctrl:1
	v_max_f32_e32 v4, v4, v4
	v_max_f32_e32 v3, v3, v4
	s_nop 1
	v_mov_b32_dpp v4, v3 quad_perm:[2,3,0,1] row_mask:0xf bank_mask:0xf bound_ctrl:1
	v_max_f32_e32 v4, v4, v4
	v_max_f32_e32 v3, v3, v4
	s_nop 1
	v_mov_b32_dpp v4, v3 row_half_mirror row_mask:0xf bank_mask:0xf bound_ctrl:1
	v_max_f32_e32 v4, v4, v4
	v_max_f32_e32 v3, v3, v4
	s_nop 1
	v_mov_b32_dpp v4, v3 row_mirror row_mask:0xf bank_mask:0xf bound_ctrl:1
	v_max_f32_e32 v4, v4, v4
	v_max_f32_e32 v3, v3, v4
	s_nop 0
	v_readlane_b32 s0, v3, 0
	v_readlane_b32 s1, v3, 16
	v_readlane_b32 s10, v3, 32
	v_readlane_b32 s11, v3, 48
	v_max_f32_e64 v3, s1, s1
	v_max_f32_e64 v4, s0, s0
	v_max_f32_e32 v3, v4, v3
	v_max_f32_e64 v4, s11, s11
	v_max_f32_e64 v5, s10, s10
	v_max_f32_e32 v4, v5, v4
	s_mov_b32 s0, 0xda24260
	v_max3_f32 v3, v3, v4, s0
	s_mov_b64 s[0:1], exec
	v_readlane_b32 s10, v254, 21
	v_readlane_b32 s11, v254, 22
	s_and_b64 s[10:11], s[0:1], s[10:11]
	s_mov_b64 exec, s[10:11]
	v_mul_f32_e32 v4, 0x3b888889, v3
	v_mov_b32_e32 v5, s93
	ds_write_b32 v5, v4 offset:14360
	s_or_b64 exec, exec, s[0:1]
	s_mov_b32 s10, 0x43700000
	v_div_scale_f32 v4, s[0:1], v3, v3, s10
	v_rcp_f32_e32 v5, v4
	s_mov_b32 s0, 0x7020c0c
	v_fma_f32 v6, -v4, v5, 1.0
	v_fmac_f32_e32 v5, v6, v5
	v_div_scale_f32 v6, vcc, s10, v3, s10
	v_mul_f32_e32 v7, v6, v5
	v_fma_f32 v8, -v4, v7, v6
	v_fmac_f32_e32 v7, v8, v5
	v_fma_f32 v4, -v4, v7, v6
	v_div_fmas_f32 v4, v4, v5, v7
	v_div_fixup_f32 v3, v4, v3, s10
	v_mul_f32_e32 v4, v3, v1
	v_mul_f32_e32 v5, v3, v2
	v_mov_b32_e32 v6, v155
	v_cvt_pk_fp8_f32 v6, v4, v5
	v_cvt_pk_f32_fp8_e32 v[4:5], v6
	v_fma_f32 v1, v3, v1, -v4
	v_fma_f32 v2, v3, v2, -v5
	v_mov_b32_e32 v4, v155
	v_cvt_pk_fp8_f32 v4, v1, v2
	ds_read2st64_b32 v[2:3], v178 offset0:36 offset1:37
	v_lshlrev_b32_e32 v1, 16, v6
	v_and_b32_e32 v1, 0xff0000, v1
	v_lshlrev_b32_e32 v5, 24, v4
	v_lshlrev_b32_e32 v4, 16, v4
	s_waitcnt lgkmcnt(0)
	v_or3_b32 v1, v2, v1, v5
	v_lshlrev_b32_e32 v2, 8, v6
	v_perm_b32 v2, v4, v2, s0
	v_or_b32_e32 v2, v2, v3
	ds_write2st64_b32 v178, v1, v2 offset0:38 offset1:39
	ds_read2st64_b32 v[2:3], v178 offset0:44 offset1:45
	ds_read2st64_b32 v[4:5], v178 offset0:46 offset1:47
	s_mov_b32 s0, 0x3e6d3388
	s_waitcnt lgkmcnt(0)
	v_fma_f32 v1, |v4|, s0, 1.0
	v_rcp_f32_e32 v1, v1
	v_cmp_gt_f32_e32 vcc, 0, v4
	v_fmamk_f32 v6, v1, 0x3f07dc22, v210
	v_fmaak_f32 v6, v1, v6, 0x3f35f0e3
	v_fmaak_f32 v6, v1, v6, 0xbe11a98e
	v_fmaak_f32 v6, v1, v6, 0x3e027906
	v_mul_f32_e32 v1, v1, v6
	v_mul_f32_e32 v6, v4, v4
	v_mul_f32_e32 v6, 0xbf38aa3b, v6
	v_exp_f32_e32 v6, v6
	s_nop 0
	v_mul_f32_e32 v1, v6, v1
	v_mul_f32_e32 v6, v4, v1
	v_fma_f32 v1, -v4, v1, v4
	v_cndmask_b32_e32 v1, v1, v6, vcc
	v_mul_f32_e32 v1, v2, v1
	v_fma_f32 v2, |v5|, s0, 1.0
	v_rcp_f32_e32 v2, v2
	v_cmp_gt_f32_e32 vcc, 0, v5
	v_fmamk_f32 v4, v2, 0x3f07dc22, v210
	v_fmaak_f32 v4, v2, v4, 0x3f35f0e3
	v_fmaak_f32 v4, v2, v4, 0xbe11a98e
	v_fmaak_f32 v4, v2, v4, 0x3e027906
	v_mul_f32_e32 v2, v2, v4
	v_mul_f32_e32 v4, v5, v5
	v_mul_f32_e32 v4, 0xbf38aa3b, v4
	v_exp_f32_e32 v4, v4
	s_nop 0
	v_mul_f32_e32 v2, v4, v2
	v_mul_f32_e32 v4, v5, v2
	v_fma_f32 v2, -v5, v2, v5
	v_cndmask_b32_e32 v2, v2, v4, vcc
	v_mul_f32_e32 v2, v3, v2
	v_max_f32_e64 v3, |v1|, |v2|
	s_nop 1
	v_mov_b32_dpp v4, v3 quad_perm:[1,0,3,2] row_mask:0xf bank_mask:0xf bound_ctrl:1
	v_max_f32_e32 v4, v4, v4
	v_max_f32_e32 v3, v3, v4
	s_nop 1
	v_mov_b32_dpp v4, v3 quad_perm:[2,3,0,1] row_mask:0xf bank_mask:0xf bound_ctrl:1
	v_max_f32_e32 v4, v4, v4
	v_max_f32_e32 v3, v3, v4
	s_nop 1
	v_mov_b32_dpp v4, v3 row_half_mirror row_mask:0xf bank_mask:0xf bound_ctrl:1
	v_max_f32_e32 v4, v4, v4
	v_max_f32_e32 v3, v3, v4
	s_nop 1
	v_mov_b32_dpp v4, v3 row_mirror row_mask:0xf bank_mask:0xf bound_ctrl:1
	v_max_f32_e32 v4, v4, v4
	v_max_f32_e32 v3, v3, v4
	s_nop 0
	v_readlane_b32 s0, v3, 0
	v_readlane_b32 s1, v3, 16
	v_readlane_b32 s10, v3, 32
	v_readlane_b32 s11, v3, 48
	v_max_f32_e64 v3, s1, s1
	v_max_f32_e64 v4, s0, s0
	v_max_f32_e32 v3, v4, v3
	v_max_f32_e64 v4, s11, s11
	v_max_f32_e64 v5, s10, s10
	v_max_f32_e32 v4, v5, v4
	s_mov_b32 s0, 0xda24260
	v_max3_f32 v3, v3, v4, s0
	s_mov_b64 s[0:1], exec
	v_readlane_b32 s10, v254, 21
	v_readlane_b32 s11, v254, 22
	s_and_b64 s[10:11], s[0:1], s[10:11]
	s_mov_b64 exec, s[10:11]
	v_mul_f32_e32 v4, 0x3b888889, v3
	v_mov_b32_e32 v5, s93
	ds_write_b32 v5, v4 offset:14364
	s_or_b64 exec, exec, s[0:1]
	s_mov_b32 s10, 0x43700000
	v_div_scale_f32 v4, s[0:1], v3, v3, s10
	v_rcp_f32_e32 v5, v4
	s_mov_b32 s0, 0x7020c0c
	v_readlane_b32 s12, v254, 29
	v_fma_f32 v6, -v4, v5, 1.0
	v_fmac_f32_e32 v5, v6, v5
	v_div_scale_f32 v6, vcc, s10, v3, s10
	v_mul_f32_e32 v7, v6, v5
	v_fma_f32 v8, -v4, v7, v6
	v_fmac_f32_e32 v7, v8, v5
	v_fma_f32 v4, -v4, v7, v6
	v_div_fmas_f32 v4, v4, v5, v7
	v_div_fixup_f32 v3, v4, v3, s10
	v_mul_f32_e32 v4, v3, v1
	v_mul_f32_e32 v5, v3, v2
	v_mov_b32_e32 v6, v155
	v_cvt_pk_fp8_f32 v6, v4, v5
	s_mov_b32 s10, 0
	v_cvt_pk_f32_fp8_e32 v[4:5], v6
	v_fma_f32 v1, v3, v1, -v4
	v_fma_f32 v2, v3, v2, -v5
	v_mov_b32_e32 v4, v155
	v_cvt_pk_fp8_f32 v4, v1, v2
	ds_read2st64_b32 v[2:3], v178 offset0:42 offset1:43
	v_lshlrev_b32_e32 v1, 16, v6
	v_and_b32_e32 v1, 0xff0000, v1
	v_lshlrev_b32_e32 v5, 24, v4
	v_lshlrev_b32_e32 v4, 16, v4
	s_waitcnt lgkmcnt(0)
	v_or3_b32 v1, v2, v1, v5
	v_lshlrev_b32_e32 v2, 8, v6
	v_perm_b32 v2, v4, v2, s0
	s_add_i32 s0, s40, 0xffffe000
	s_lshr_b32 s0, s0, 12
	s_add_i32 s0, s0, 1
	s_cmpk_gt_i32 s40, 0x1fff
	s_cselect_b32 s11, s0, 0
	v_readlane_b32 s0, v254, 20
	s_mul_i32 s0, s0, 3
	s_add_i32 s11, s11, s0
	v_or_b32_e32 v2, v2, v3
	s_mul_i32 s1, s11, 0x6000
	ds_write2st64_b32 v178, v1, v2 offset0:44 offset1:45
	s_mul_hi_u32 s0, s11, 0x6000
	s_add_u32 s1, s12, s1
	v_readlane_b32 s12, v254, 30
	s_waitcnt lgkmcnt(0)
	s_addc_u32 s12, s12, s0
	s_add_u32 s0, s1, 0x5000
	s_addc_u32 s1, s12, 0
